# page items in P1 tail on WG>=100
# baseline (speedup 1.0000x reference)
.LBB0_7:
	s_nop 0
	v_readlane_b32 s0, v254, 2
	v_readlane_b32 s1, v254, 3
	v_writelane_b32 v254, s48, 40
	s_cmp_lt_i32 s0, 1
	s_cselect_b64 s[4:5], -1, 0
	v_writelane_b32 v254, s49, 41
	v_writelane_b32 v254, s50, 42
	s_cmp_gt_i32 s1, 0
	v_writelane_b32 v254, s51, 43
	s_cselect_b64 s[6:7], -1, 0
	v_writelane_b32 v254, s52, 44
	s_and_b64 s[6:7], s[4:5], s[6:7]
	v_writelane_b32 v254, s53, 45
	s_andn2_b64 vcc, exec, s[6:7]
	v_and_b32_e32 v206, 63, v0
	v_writelane_b32 v254, s54, 46
	v_writelane_b32 v254, s55, 47
	s_cbranch_vccnz .LBB0_113
	s_movk_i32 s98, 0x2a7f
	v_readlane_b32 s0, v254, 0
	v_readlane_b32 s1, v254, 1
	s_load_dword s8, s[0:1], 0xe8
	v_readfirstlane_b32 s0, v0
	s_lshr_b32 s9, s0, 6
	s_lshl_b32 s0, s2, 3
	s_add_i32 s10, s9, s0
	s_waitcnt lgkmcnt(0)
	s_cmp_le_u32 s8, 100
	s_cbranch_scc1 .Lrc_nb
	s_sub_u32 s0, s8, 100
	s_lshl_b32 s0, s0, 3
	s_sub_u32 s98, s98, s0

.LBB0_325:
	s_cmp_eq_u32 s99, 5
	s_cbranch_scc0 .Lrc_p1skip
	s_cmp_lt_u32 s100, 100
	s_cbranch_scc1 .Lrc_p1skip
	s_mov_b32 s99, 7
	s_mov_b64 exec, -1
	v_readlane_b32 s0, v254, 0
	v_readlane_b32 s1, v254, 1
	v_readlane_b32 s52, v254, 44
	v_readlane_b32 s53, v254, 45
	v_readlane_b32 s54, v254, 46
	v_readlane_b32 s55, v254, 47
	s_nop 4
	s_load_dwordx16 s[76:91], s[0:1], 0x0
	s_load_dword s8, s[0:1], 0xe8
	s_waitcnt lgkmcnt(0)
	s_add_u32 s2, s100, 0x550
	s_sub_u32 s2, s2, s8
	s_sub_u32 s8, s8, 100
	s_movk_i32 s98, 0x2a7f
	v_readfirstlane_b32 s9, v0
	s_lshr_b32 s9, s9, 6
	s_lshl_b32 s10, s2, 3
	s_add_u32 s10, s10, s9
	s_lshl_b32 s3, s8, 3
	v_and_b32_e32 v34, 63, v0
	s_branch .LBB0_78
